# nomidprio plus nt hint on the phase-0 bf16 weight/x stores
# baseline (speedup 1.0000x reference)
.LBB0_291:
	s_cmpk_lt_i32 s24, 0x2230
	s_cselect_b64 s[40:41], -1, 0
	s_lshr_b32 s4, s34, 7
	v_cvt_f32_u32_e32 v102, s4
	s_sub_i32 s34, 0, s4
	s_abs_i32 s30, s61
	s_ashr_i32 s5, s61, 31
	v_rcp_iflag_f32_e32 v102, v102
	s_nop 0
	v_mul_f32_e32 v102, 0x4f7ffffe, v102
	v_cvt_u32_f32_e32 v102, v102
	s_nop 0
	v_readfirstlane_b32 s35, v102
	s_mul_i32 s34, s34, s35
	s_mul_hi_u32 s34, s35, s34
	s_add_i32 s35, s35, s34
	s_mul_hi_u32 s34, s30, s35
	s_mul_i32 s35, s34, s4
	s_sub_i32 s30, s30, s35
	s_add_i32 s38, s34, 1
	s_sub_i32 s35, s30, s4
	s_cmp_ge_u32 s30, s4
	s_cselect_b32 s34, s38, s34
	s_cselect_b32 s30, s35, s30
	s_add_i32 s35, s34, 1
	s_cmp_ge_u32 s30, s4
	s_cselect_b32 s30, s35, s34
	s_xor_b32 s30, s30, s5
	s_sub_i32 s5, s30, s5
	s_mul_i32 s4, s5, s4
	s_sub_i32 s4, s61, s4
	s_lshl_b32 s30, s4, 1
	s_add_i32 s34, s30, 0x1ffffab
	s_cmp_lt_i32 s4, 43
	s_cselect_b32 s30, s30, s34
	s_cmp_eq_u32 s31, 0
	s_cselect_b32 s30, s4, s30
	s_lshl_b32 s30, s30, 7
	ds_read_u16 v102, v109
	ds_read_u16 v105, v109 offset:260
	ds_read_u16 v106, v109 offset:520
	ds_read_u16 v107, v109 offset:780
	ds_read_u16 v148, v109 offset:1040
	ds_read_u16 v149, v109 offset:1300
	ds_read_u16 v150, v109 offset:1560
	ds_read_u16 v151, v109 offset:1820
	s_add_i32 s34, s30, s63
	s_waitcnt lgkmcnt(6)
	v_lshl_or_b32 v146, v105, 16, v102
	v_add_u32_e32 v102, s34, v108
	s_waitcnt lgkmcnt(4)
	v_lshl_or_b32 v147, v107, 16, v106
	v_mad_u64_u32 v[106:107], s[30:31], v102, s62, 0
	v_ashrrev_i32_e32 v105, 31, v102
	v_mov_b32_e32 v102, v107
	s_lshl_b32 s4, s5, 7
	s_waitcnt lgkmcnt(2)
	v_lshl_or_b32 v148, v149, 16, v148
	s_waitcnt lgkmcnt(0)
	v_lshl_or_b32 v149, v151, 16, v150
	v_mad_u64_u32 v[150:151], s[30:31], v105, s62, v[102:103]
	s_ashr_i32 s5, s4, 31
	v_mov_b32_e32 v107, v150
	s_lshl_b64 s[4:5], s[4:5], 1
	v_lshl_add_u64 v[106:107], v[106:107], 1, s[28:29]
	v_lshl_add_u64 v[106:107], v[106:107], 0, s[4:5]
	v_mov_b32_e32 v105, v103
	v_lshl_add_u64 v[106:107], v[106:107], 0, v[104:105]
	ds_read_u16 v102, v111
	ds_read_u16 v150, v111 offset:260
	ds_read_u16 v151, v111 offset:520
	ds_read_u16 v152, v111 offset:780
	ds_read_u16 v153, v111 offset:1040
	ds_read_u16 v154, v111 offset:1300
	ds_read_u16 v155, v111 offset:1560
	ds_read_u16 v156, v111 offset:1820
	global_store_dwordx4 v[106:107], v[146:149], off nt
	s_cmpk_gt_i32 s24, 0x222f
	s_waitcnt lgkmcnt(6)
	v_lshl_or_b32 v146, v150, 16, v102
	v_add_u32_e32 v102, s34, v110
	v_mad_u64_u32 v[106:107], s[30:31], v102, s62, 0
	v_ashrrev_i32_e32 v150, 31, v102
	v_mov_b32_e32 v102, v107
	s_waitcnt lgkmcnt(4)
	v_lshl_or_b32 v147, v152, 16, v151
	v_mad_u64_u32 v[150:151], s[30:31], v150, s62, v[102:103]
	v_mov_b32_e32 v107, v150
	v_lshl_add_u64 v[106:107], v[106:107], 1, s[28:29]
	v_lshl_add_u64 v[106:107], v[106:107], 0, s[4:5]
	s_waitcnt lgkmcnt(2)
	v_lshl_or_b32 v148, v154, 16, v153
	s_waitcnt lgkmcnt(0)
	v_lshl_or_b32 v149, v156, 16, v155
	v_lshl_add_u64 v[106:107], v[106:107], 0, v[104:105]
	ds_read_u16 v102, v113
	ds_read_u16 v150, v113 offset:260
	ds_read_u16 v151, v113 offset:520
	ds_read_u16 v152, v113 offset:780
	ds_read_u16 v153, v113 offset:1040
	ds_read_u16 v154, v113 offset:1300
	ds_read_u16 v155, v113 offset:1560
	ds_read_u16 v156, v113 offset:1820
	global_store_dwordx4 v[106:107], v[146:149], off nt
	s_waitcnt lgkmcnt(6)
	s_nop 0
	v_lshl_or_b32 v146, v150, 16, v102
	v_add_u32_e32 v102, s34, v112
	v_mad_u64_u32 v[106:107], s[30:31], v102, s62, 0
	v_ashrrev_i32_e32 v150, 31, v102
	v_mov_b32_e32 v102, v107
	s_waitcnt lgkmcnt(4)
	v_lshl_or_b32 v147, v152, 16, v151
	v_mad_u64_u32 v[150:151], s[30:31], v150, s62, v[102:103]
	v_mov_b32_e32 v107, v150
	v_lshl_add_u64 v[106:107], v[106:107], 1, s[28:29]
	v_lshl_add_u64 v[106:107], v[106:107], 0, s[4:5]
	s_waitcnt lgkmcnt(2)
	v_lshl_or_b32 v148, v154, 16, v153
	s_waitcnt lgkmcnt(0)
	v_lshl_or_b32 v149, v156, 16, v155
	v_lshl_add_u64 v[106:107], v[106:107], 0, v[104:105]
	ds_read_u16 v102, v115
	ds_read_u16 v150, v115 offset:260
	ds_read_u16 v151, v115 offset:520
	ds_read_u16 v152, v115 offset:780
	ds_read_u16 v153, v115 offset:1040
	ds_read_u16 v154, v115 offset:1300
	ds_read_u16 v155, v115 offset:1560
	ds_read_u16 v156, v115 offset:1820
	global_store_dwordx4 v[106:107], v[146:149], off nt
	s_waitcnt lgkmcnt(6)
	s_nop 0
	v_lshl_or_b32 v146, v150, 16, v102
	v_add_u32_e32 v102, s34, v114
	v_mad_u64_u32 v[106:107], s[30:31], v102, s62, 0
	v_ashrrev_i32_e32 v150, 31, v102
	v_mov_b32_e32 v102, v107
	s_waitcnt lgkmcnt(4)
	v_lshl_or_b32 v147, v152, 16, v151
	v_mad_u64_u32 v[150:151], s[30:31], v150, s62, v[102:103]
	v_mov_b32_e32 v107, v150
	v_lshl_add_u64 v[106:107], v[106:107], 1, s[28:29]
	v_lshl_add_u64 v[106:107], v[106:107], 0, s[4:5]
	s_waitcnt lgkmcnt(2)
	v_lshl_or_b32 v148, v154, 16, v153
	s_waitcnt lgkmcnt(0)
	v_lshl_or_b32 v149, v156, 16, v155
	v_lshl_add_u64 v[106:107], v[106:107], 0, v[104:105]
	global_store_dwordx4 v[106:107], v[146:149], off nt
	s_cbranch_scc1 .LBB0_293
	v_mul_f32_e32 v102, v131, v34
	v_mul_f32_e32 v105, v131, v35
	v_cvt_pk_bf16_f32 v102, v102, v105
	ds_write_b32 v120, v102 offset:33280
	v_mul_f32_e32 v102, v131, v36
	v_mul_f32_e32 v105, v131, v37
	v_cvt_pk_bf16_f32 v102, v102, v105
	ds_write_b32 v120, v102 offset:33284
	v_mul_f32_e32 v102, v132, v38
	v_mul_f32_e32 v105, v132, v39
	v_cvt_pk_bf16_f32 v102, v102, v105
	ds_write_b32 v120, v102 offset:37440
	v_mul_f32_e32 v102, v132, v40
	v_mul_f32_e32 v105, v132, v41
	v_cvt_pk_bf16_f32 v102, v102, v105
	ds_write_b32 v120, v102 offset:37444
	v_mul_f32_e32 v102, v130, v42
	v_mul_f32_e32 v105, v130, v43
	v_cvt_pk_bf16_f32 v102, v102, v105
	ds_write_b32 v120, v102 offset:41600
	v_mul_f32_e32 v102, v130, v44
	v_mul_f32_e32 v105, v130, v45
	v_cvt_pk_bf16_f32 v102, v102, v105
	ds_write_b32 v120, v102 offset:41604
	v_mul_f32_e32 v102, v133, v46
	v_mul_f32_e32 v105, v133, v47
	v_cvt_pk_bf16_f32 v102, v102, v105
	ds_write_b32 v120, v102 offset:45760
	v_mul_f32_e32 v102, v133, v48
	v_mul_f32_e32 v105, v133, v49
	v_cvt_pk_bf16_f32 v102, v102, v105
	ds_write_b32 v120, v102 offset:45764
	v_mul_f32_e32 v102, v135, v50
	v_mul_f32_e32 v105, v135, v51
	v_cvt_pk_bf16_f32 v102, v102, v105
	ds_write_b32 v120, v102 offset:49920
	v_mul_f32_e32 v102, v135, v52
	v_mul_f32_e32 v105, v135, v53
	v_cvt_pk_bf16_f32 v102, v102, v105
	ds_write_b32 v120, v102 offset:49924
	v_mul_f32_e32 v102, v136, v54
	v_mul_f32_e32 v105, v136, v55
	v_cvt_pk_bf16_f32 v102, v102, v105
	ds_write_b32 v120, v102 offset:54080
	v_mul_f32_e32 v102, v136, v56
	v_mul_f32_e32 v105, v136, v57
	v_cvt_pk_bf16_f32 v102, v102, v105
	ds_write_b32 v120, v102 offset:54084
	v_mul_f32_e32 v102, v137, v58
	v_mul_f32_e32 v105, v137, v59
	v_cvt_pk_bf16_f32 v102, v102, v105
	ds_write_b32 v120, v102 offset:58240
	v_mul_f32_e32 v102, v137, v60
	v_mul_f32_e32 v105, v137, v61
	v_cvt_pk_bf16_f32 v102, v102, v105
	ds_write_b32 v120, v102 offset:58244
	v_mul_f32_e32 v102, v134, v62
	v_mul_f32_e32 v105, v134, v63
	v_cvt_pk_bf16_f32 v102, v102, v105
	ds_write_b32 v120, v102 offset:62400
	v_mul_f32_e32 v102, v134, v64
	v_mul_f32_e32 v105, v134, v65
	v_cvt_pk_bf16_f32 v102, v102, v105
	ds_write_b32 v120, v102 offset:62404

.LBB0_340:
	s_andn2_b64 vcc, exec, s[40:41]
	s_cbranch_vccnz .LBB0_342
	s_lshr_b32 s4, s26, 7
	v_cvt_f32_u32_e32 v102, s4
	s_sub_i32 s26, 0, s4
	s_abs_i32 s24, s58
	s_ashr_i32 s5, s58, 31
	v_rcp_iflag_f32_e32 v102, v102
	s_nop 0
	v_mul_f32_e32 v102, 0x4f7ffffe, v102
	v_cvt_u32_f32_e32 v102, v102
	s_nop 0
	v_readfirstlane_b32 s28, v102
	s_mul_i32 s26, s26, s28
	s_mul_hi_u32 s26, s28, s26
	s_add_i32 s28, s28, s26
	s_mul_hi_u32 s26, s24, s28
	s_mul_i32 s28, s26, s4
	s_sub_i32 s24, s24, s28
	s_add_i32 s29, s26, 1
	s_sub_i32 s28, s24, s4
	s_cmp_ge_u32 s24, s4
	s_cselect_b32 s26, s29, s26
	s_cselect_b32 s24, s28, s24
	s_add_i32 s28, s26, 1
	s_cmp_ge_u32 s24, s4
	s_cselect_b32 s24, s28, s26
	s_xor_b32 s24, s24, s5
	s_sub_i32 s5, s24, s5
	s_mul_i32 s4, s5, s4
	s_sub_i32 s4, s58, s4
	s_lshl_b32 s24, s4, 1
	s_add_i32 s26, s24, 0x1ffffab
	s_cmp_lt_i32 s4, 43
	s_cselect_b32 s24, s24, s26
	s_cmp_eq_u32 s25, 0
	s_cselect_b32 s24, s4, s24
	s_lshl_b32 s24, s24, 7
	ds_read_u16 v102, v109 offset:33280
	ds_read_u16 v105, v109 offset:33540
	ds_read_u16 v106, v109 offset:33800
	ds_read_u16 v107, v109 offset:34060
	ds_read_u16 v148, v109 offset:34320
	ds_read_u16 v149, v109 offset:34580
	ds_read_u16 v150, v109 offset:34840
	ds_read_u16 v151, v109 offset:35100
	s_add_i32 s26, s24, s60
	s_waitcnt lgkmcnt(6)
	v_lshl_or_b32 v146, v105, 16, v102
	v_add_u32_e32 v102, s26, v108
	s_waitcnt lgkmcnt(4)
	v_lshl_or_b32 v147, v107, 16, v106
	v_mad_u64_u32 v[106:107], s[24:25], v102, s59, 0
	v_ashrrev_i32_e32 v105, 31, v102
	v_mov_b32_e32 v102, v107
	s_lshl_b32 s4, s5, 7
	s_waitcnt lgkmcnt(2)
	v_lshl_or_b32 v148, v149, 16, v148
	s_waitcnt lgkmcnt(0)
	v_lshl_or_b32 v149, v151, 16, v150
	v_mad_u64_u32 v[150:151], s[24:25], v105, s59, v[102:103]
	s_ashr_i32 s5, s4, 31
	v_mov_b32_e32 v107, v150
	v_lshl_add_u64 v[106:107], v[106:107], 1, s[22:23]
	s_lshl_b64 s[4:5], s[4:5], 1
	v_lshl_add_u64 v[106:107], v[106:107], 0, s[4:5]
	v_mov_b32_e32 v105, v103
	v_lshl_add_u64 v[106:107], v[106:107], 0, v[104:105]
	ds_read_u16 v102, v111 offset:33280
	ds_read_u16 v150, v111 offset:33540
	ds_read_u16 v151, v111 offset:33800
	ds_read_u16 v152, v111 offset:34060
	ds_read_u16 v153, v111 offset:34320
	ds_read_u16 v154, v111 offset:34580
	ds_read_u16 v155, v111 offset:34840
	ds_read_u16 v156, v111 offset:35100
	global_store_dwordx4 v[106:107], v[146:149], off nt
	s_waitcnt lgkmcnt(6)
	s_nop 0
	v_lshl_or_b32 v146, v150, 16, v102
	v_add_u32_e32 v102, s26, v110
	v_mad_u64_u32 v[106:107], s[24:25], v102, s59, 0
	v_ashrrev_i32_e32 v150, 31, v102
	v_mov_b32_e32 v102, v107
	s_waitcnt lgkmcnt(4)
	v_lshl_or_b32 v147, v152, 16, v151
	v_mad_u64_u32 v[150:151], s[24:25], v150, s59, v[102:103]
	v_mov_b32_e32 v107, v150
	v_lshl_add_u64 v[106:107], v[106:107], 1, s[22:23]
	v_lshl_add_u64 v[106:107], v[106:107], 0, s[4:5]
	s_waitcnt lgkmcnt(2)
	v_lshl_or_b32 v148, v154, 16, v153
	s_waitcnt lgkmcnt(0)
	v_lshl_or_b32 v149, v156, 16, v155
	v_lshl_add_u64 v[106:107], v[106:107], 0, v[104:105]
	ds_read_u16 v102, v113 offset:33280
	ds_read_u16 v150, v113 offset:33540
	ds_read_u16 v151, v113 offset:33800
	ds_read_u16 v152, v113 offset:34060
	ds_read_u16 v153, v113 offset:34320
	ds_read_u16 v154, v113 offset:34580
	ds_read_u16 v155, v113 offset:34840
	ds_read_u16 v156, v113 offset:35100
	global_store_dwordx4 v[106:107], v[146:149], off nt
	s_waitcnt lgkmcnt(6)
	s_nop 0
	v_lshl_or_b32 v146, v150, 16, v102
	v_add_u32_e32 v102, s26, v112
	v_mad_u64_u32 v[106:107], s[24:25], v102, s59, 0
	v_ashrrev_i32_e32 v150, 31, v102
	v_mov_b32_e32 v102, v107
	s_waitcnt lgkmcnt(4)
	v_lshl_or_b32 v147, v152, 16, v151
	v_mad_u64_u32 v[150:151], s[24:25], v150, s59, v[102:103]
	v_mov_b32_e32 v107, v150
	v_lshl_add_u64 v[106:107], v[106:107], 1, s[22:23]
	v_lshl_add_u64 v[106:107], v[106:107], 0, s[4:5]
	s_waitcnt lgkmcnt(2)
	v_lshl_or_b32 v148, v154, 16, v153
	s_waitcnt lgkmcnt(0)
	v_lshl_or_b32 v149, v156, 16, v155
	v_lshl_add_u64 v[106:107], v[106:107], 0, v[104:105]
	ds_read_u16 v102, v115 offset:33280
	ds_read_u16 v150, v115 offset:33540
	ds_read_u16 v151, v115 offset:33800
	ds_read_u16 v152, v115 offset:34060
	ds_read_u16 v153, v115 offset:34320
	ds_read_u16 v154, v115 offset:34580
	ds_read_u16 v155, v115 offset:34840
	ds_read_u16 v156, v115 offset:35100
	global_store_dwordx4 v[106:107], v[146:149], off nt
	s_waitcnt lgkmcnt(6)
	s_nop 0
	v_lshl_or_b32 v146, v150, 16, v102
	v_add_u32_e32 v102, s26, v114
	v_mad_u64_u32 v[106:107], s[24:25], v102, s59, 0
	v_ashrrev_i32_e32 v150, 31, v102
	v_mov_b32_e32 v102, v107
	s_waitcnt lgkmcnt(4)
	v_lshl_or_b32 v147, v152, 16, v151
	v_mad_u64_u32 v[150:151], s[24:25], v150, s59, v[102:103]
	v_mov_b32_e32 v107, v150
	v_lshl_add_u64 v[106:107], v[106:107], 1, s[22:23]
	v_lshl_add_u64 v[106:107], v[106:107], 0, s[4:5]
	s_waitcnt lgkmcnt(2)
	v_lshl_or_b32 v148, v154, 16, v153
	s_waitcnt lgkmcnt(0)
	v_lshl_or_b32 v149, v156, 16, v155
	v_lshl_add_u64 v[106:107], v[106:107], 0, v[104:105]
	global_store_dwordx4 v[106:107], v[146:149], off nt

.LBB0_391:
	s_andn2_b64 vcc, exec, s[22:23]
	s_cbranch_vccnz .LBB0_227
	s_lshr_b32 s4, s18, 7
	v_cvt_f32_u32_e32 v102, s4
	s_sub_i32 s22, 0, s4
	s_abs_i32 s18, s55
	s_ashr_i32 s5, s55, 31
	v_rcp_iflag_f32_e32 v102, v102
	s_nop 0
	v_mul_f32_e32 v102, 0x4f7ffffe, v102
	v_cvt_u32_f32_e32 v102, v102
	s_nop 0
	v_readfirstlane_b32 s23, v102
	s_mul_i32 s22, s22, s23
	s_mul_hi_u32 s22, s23, s22
	s_add_i32 s23, s23, s22
	s_mul_hi_u32 s22, s18, s23
	s_mul_i32 s23, s22, s4
	s_sub_i32 s18, s18, s23
	s_add_i32 s25, s22, 1
	s_sub_i32 s23, s18, s4
	s_cmp_ge_u32 s18, s4
	s_cselect_b32 s22, s25, s22
	s_cselect_b32 s18, s23, s18
	s_add_i32 s23, s22, 1
	s_cmp_ge_u32 s18, s4
	s_cselect_b32 s18, s23, s22
	s_xor_b32 s18, s18, s5
	s_sub_i32 s5, s18, s5
	s_mul_i32 s4, s5, s4
	s_sub_i32 s4, s55, s4
	s_lshl_b32 s18, s4, 1
	s_add_i32 s22, s18, 0x1ffffab
	s_cmp_lt_i32 s4, 43
	s_cselect_b32 s18, s18, s22
	s_cmp_eq_u32 s17, 0
	s_cselect_b32 s17, s4, s18
	s_lshl_b32 s17, s17, 7
	ds_read_u16 v102, v116
	ds_read_u16 v105, v116 offset:260
	ds_read_u16 v106, v116 offset:520
	ds_read_u16 v107, v116 offset:780
	ds_read_u16 v148, v116 offset:1040
	ds_read_u16 v149, v116 offset:1300
	ds_read_u16 v150, v116 offset:1560
	ds_read_u16 v151, v116 offset:1820
	s_add_i32 s17, s17, s57
	s_waitcnt lgkmcnt(6)
	v_lshl_or_b32 v146, v105, 16, v102
	v_add_u32_e32 v102, s17, v108
	s_waitcnt lgkmcnt(4)
	v_lshl_or_b32 v147, v107, 16, v106
	v_mad_u64_u32 v[106:107], s[22:23], v102, s56, 0
	v_ashrrev_i32_e32 v105, 31, v102
	v_mov_b32_e32 v102, v107
	s_lshl_b32 s4, s5, 7
	s_waitcnt lgkmcnt(2)
	v_lshl_or_b32 v148, v149, 16, v148
	s_waitcnt lgkmcnt(0)
	v_lshl_or_b32 v149, v151, 16, v150
	v_mad_u64_u32 v[150:151], s[22:23], v105, s56, v[102:103]
	s_ashr_i32 s5, s4, 31
	v_mov_b32_e32 v107, v150
	v_lshl_add_u64 v[106:107], v[106:107], 1, s[8:9]
	s_lshl_b64 s[4:5], s[4:5], 1
	v_lshl_add_u64 v[106:107], v[106:107], 0, s[4:5]
	v_mov_b32_e32 v105, v103
	v_lshl_add_u64 v[106:107], v[106:107], 0, v[104:105]
	ds_read_u16 v102, v117
	ds_read_u16 v150, v117 offset:260
	ds_read_u16 v151, v117 offset:520
	ds_read_u16 v152, v117 offset:780
	ds_read_u16 v153, v117 offset:1040
	ds_read_u16 v154, v117 offset:1300
	ds_read_u16 v155, v117 offset:1560
	ds_read_u16 v156, v117 offset:1820
	global_store_dwordx4 v[106:107], v[146:149], off nt
	s_waitcnt lgkmcnt(6)
	s_nop 0
	v_lshl_or_b32 v146, v150, 16, v102
	v_add_u32_e32 v102, s17, v110
	v_mad_u64_u32 v[106:107], s[22:23], v102, s56, 0
	v_ashrrev_i32_e32 v150, 31, v102
	v_mov_b32_e32 v102, v107
	s_waitcnt lgkmcnt(4)
	v_lshl_or_b32 v147, v152, 16, v151
	v_mad_u64_u32 v[150:151], s[22:23], v150, s56, v[102:103]
	v_mov_b32_e32 v107, v150
	v_lshl_add_u64 v[106:107], v[106:107], 1, s[8:9]
	v_lshl_add_u64 v[106:107], v[106:107], 0, s[4:5]
	s_waitcnt lgkmcnt(2)
	v_lshl_or_b32 v148, v154, 16, v153
	s_waitcnt lgkmcnt(0)
	v_lshl_or_b32 v149, v156, 16, v155
	v_lshl_add_u64 v[106:107], v[106:107], 0, v[104:105]
	ds_read_u16 v102, v118
	ds_read_u16 v150, v118 offset:260
	ds_read_u16 v151, v118 offset:520
	ds_read_u16 v152, v118 offset:780
	ds_read_u16 v153, v118 offset:1040
	ds_read_u16 v154, v118 offset:1300
	ds_read_u16 v155, v118 offset:1560
	ds_read_u16 v156, v118 offset:1820
	global_store_dwordx4 v[106:107], v[146:149], off nt
	s_waitcnt lgkmcnt(6)
	s_nop 0
	v_lshl_or_b32 v146, v150, 16, v102
	v_add_u32_e32 v102, s17, v112
	v_mad_u64_u32 v[106:107], s[22:23], v102, s56, 0
	v_ashrrev_i32_e32 v150, 31, v102
	v_mov_b32_e32 v102, v107
	s_waitcnt lgkmcnt(4)
	v_lshl_or_b32 v147, v152, 16, v151
	v_mad_u64_u32 v[150:151], s[22:23], v150, s56, v[102:103]
	v_mov_b32_e32 v107, v150
	v_lshl_add_u64 v[106:107], v[106:107], 1, s[8:9]
	v_lshl_add_u64 v[106:107], v[106:107], 0, s[4:5]
	s_waitcnt lgkmcnt(2)
	v_lshl_or_b32 v148, v154, 16, v153
	s_waitcnt lgkmcnt(0)
	v_lshl_or_b32 v149, v156, 16, v155
	v_lshl_add_u64 v[106:107], v[106:107], 0, v[104:105]
	ds_read_u16 v102, v119
	ds_read_u16 v150, v119 offset:260
	ds_read_u16 v151, v119 offset:520
	ds_read_u16 v152, v119 offset:780
	ds_read_u16 v153, v119 offset:1040
	ds_read_u16 v154, v119 offset:1300
	ds_read_u16 v155, v119 offset:1560
	ds_read_u16 v156, v119 offset:1820
	global_store_dwordx4 v[106:107], v[146:149], off nt
	s_waitcnt lgkmcnt(6)
	s_nop 0
	v_lshl_or_b32 v146, v150, 16, v102
	v_add_u32_e32 v102, s17, v114
	v_mad_u64_u32 v[106:107], s[22:23], v102, s56, 0
	v_ashrrev_i32_e32 v150, 31, v102
	v_mov_b32_e32 v102, v107
	s_waitcnt lgkmcnt(4)
	v_lshl_or_b32 v147, v152, 16, v151
	v_mad_u64_u32 v[150:151], s[22:23], v150, s56, v[102:103]
	v_mov_b32_e32 v107, v150
	v_lshl_add_u64 v[106:107], v[106:107], 1, s[8:9]
	v_lshl_add_u64 v[106:107], v[106:107], 0, s[4:5]
	s_waitcnt lgkmcnt(2)
	v_lshl_or_b32 v148, v154, 16, v153
	s_waitcnt lgkmcnt(0)
	v_lshl_or_b32 v149, v156, 16, v155
	v_lshl_add_u64 v[106:107], v[106:107], 0, v[104:105]
	global_store_dwordx4 v[106:107], v[146:149], off nt
	s_branch .LBB0_227

.LBB0_455:
	v_lshlrev_b32_e32 v68, 4, v66
	s_waitcnt lgkmcnt(0)
	v_lshl_add_u64 v[42:43], s[30:31], 0, v[68:69]
	v_add_co_u32_e32 v74, vcc, 0x1000, v42
	global_load_dwordx4 v[22:25], v68, s[30:31] nt
	global_load_dwordx4 v[26:29], v68, s[30:31] offset:1024 nt
	global_load_dwordx4 v[30:33], v68, s[30:31] offset:2048 nt
	global_load_dwordx4 v[34:37], v68, s[30:31] offset:3072 nt
	v_addc_co_u32_e32 v75, vcc, 0, v43, vcc
	global_load_dwordx4 v[42:45], v[74:75], off nt
	global_load_dwordx4 v[46:49], v[74:75], off offset:1024 nt
	global_load_dwordx4 v[50:53], v[74:75], off offset:2048 nt
	global_load_dwordx4 v[54:57], v[74:75], off offset:3072 nt
	s_mov_b64 s[28:29], -1
	s_cmpk_gt_i32 s26, 0x20ff
	v_mbcnt_hi_u32_b32 v73, -1, v72
	s_cbranch_scc0 .LBB0_459
	s_waitcnt vmcnt(8)
	v_mul_f32_e32 v68, v63, v63
	v_mul_f32_e32 v74, v65, v65
	v_fmac_f32_e32 v68, v62, v62
	v_fmac_f32_e32 v74, v64, v64
	v_add_f32_e32 v68, v68, v74
	v_mul_f32_e32 v74, v59, v59
	v_mul_f32_e32 v75, v61, v61
	v_fmac_f32_e32 v74, v58, v58
	v_fmac_f32_e32 v75, v60, v60
	v_add_f32_e32 v74, v74, v75
	v_add_f32_e32 v68, v68, v74
	v_mul_f32_e32 v74, v39, v39
	v_mul_f32_e32 v75, v41, v41
	v_fmac_f32_e32 v74, v38, v38
	v_fmac_f32_e32 v75, v40, v40
	v_add_f32_e32 v74, v74, v75
	v_add_f32_e32 v68, v68, v74
	v_mul_f32_e32 v74, v19, v19
	v_mul_f32_e32 v75, v21, v21
	v_fmac_f32_e32 v74, v18, v18
	v_fmac_f32_e32 v75, v20, v20
	v_add_f32_e32 v74, v74, v75
	v_add_f32_e32 v68, v68, v74
	v_mul_f32_e32 v74, v15, v15
	v_mul_f32_e32 v75, v17, v17
	v_fmac_f32_e32 v74, v14, v14
	v_fmac_f32_e32 v75, v16, v16
	v_add_f32_e32 v74, v74, v75
	v_add_f32_e32 v68, v68, v74
	v_mul_f32_e32 v74, v11, v11
	v_mul_f32_e32 v75, v13, v13
	v_fmac_f32_e32 v74, v10, v10
	v_fmac_f32_e32 v75, v12, v12
	v_add_f32_e32 v74, v74, v75
	v_add_f32_e32 v68, v68, v74
	v_mul_f32_e32 v74, v7, v7
	v_mul_f32_e32 v75, v9, v9
	v_fmac_f32_e32 v74, v6, v6
	v_fmac_f32_e32 v75, v8, v8
	v_add_f32_e32 v74, v74, v75
	v_add_f32_e32 v68, v68, v74
	v_mul_f32_e32 v74, v3, v3
	v_mul_f32_e32 v75, v5, v5
	v_fmac_f32_e32 v74, v2, v2
	v_fmac_f32_e32 v75, v4, v4
	v_add_f32_e32 v74, v74, v75
	v_add_f32_e32 v68, v68, v74
	v_and_b32_e32 v74, 64, v73
	v_add_u32_e32 v75, 64, v74
	v_xor_b32_e32 v74, 1, v73
	v_cmp_lt_i32_e32 vcc, v74, v75
	s_load_dwordx2 s[28:29], s[14:15], 0x118
	s_add_i32 s8, s26, 0xffffdf00
	v_cndmask_b32_e32 v74, v73, v74, vcc
	v_lshlrev_b32_e32 v74, 2, v74
	ds_bpermute_b32 v74, v74, v68
	s_lshl_b64 s[30:31], s[8:9], 12
	s_waitcnt lgkmcnt(0)
	s_add_u32 s30, s28, s30
	s_addc_u32 s31, s29, s31
	v_cvt_pk_bf16_f32 v76, v62, v63
	v_add_f32_e32 v68, v68, v74
	v_xor_b32_e32 v74, 2, v73
	v_cmp_lt_i32_e32 vcc, v74, v75
	v_cvt_pk_bf16_f32 v77, v64, v65
	s_nop 1
	v_cndmask_b32_e32 v74, v73, v74, vcc
	v_lshlrev_b32_e32 v74, 2, v74
	ds_bpermute_b32 v74, v74, v68
	s_waitcnt lgkmcnt(0)
	v_add_f32_e32 v68, v68, v74
	v_xor_b32_e32 v74, 4, v73
	v_cmp_lt_i32_e32 vcc, v74, v75
	s_nop 1
	v_cndmask_b32_e32 v74, v73, v74, vcc
	v_lshlrev_b32_e32 v74, 2, v74
	ds_bpermute_b32 v74, v74, v68
	s_waitcnt lgkmcnt(0)
	v_add_f32_e32 v68, v68, v74
	v_xor_b32_e32 v74, 8, v73
	v_cmp_lt_i32_e32 vcc, v74, v75
	s_nop 1
	v_cndmask_b32_e32 v74, v73, v74, vcc
	v_lshlrev_b32_e32 v74, 2, v74
	ds_bpermute_b32 v74, v74, v68
	s_waitcnt lgkmcnt(0)
	v_add_f32_e32 v68, v68, v74
	v_xor_b32_e32 v74, 16, v73
	v_cmp_lt_i32_e32 vcc, v74, v75
	s_nop 1
	v_cndmask_b32_e32 v74, v73, v74, vcc
	v_lshlrev_b32_e32 v74, 2, v74
	ds_bpermute_b32 v74, v74, v68
	s_waitcnt lgkmcnt(0)
	v_add_f32_e32 v74, v68, v74
	v_xor_b32_e32 v68, 32, v73
	v_cmp_lt_i32_e32 vcc, v68, v75
	s_nop 1
	v_cndmask_b32_e32 v68, v73, v68, vcc
	v_lshlrev_b32_e32 v68, 2, v68
	ds_bpermute_b32 v75, v68, v74
	v_lshlrev_b32_e32 v68, 3, v66
	v_lshl_add_u64 v[78:79], s[30:31], 0, v[68:69]
	v_lshl_add_u64 v[80:81], v[78:79], 0, s[22:23]
	v_add_co_u32_e32 v78, vcc, s7, v78
	s_nop 1
	v_addc_co_u32_e32 v79, vcc, 0, v79, vcc
	global_store_dwordx2 v[78:79], v[76:77], off nt
	v_cvt_pk_bf16_f32 v76, v58, v59
	v_cvt_pk_bf16_f32 v77, v60, v61
	global_store_dwordx2 v[80:81], v[76:77], off offset:512 nt
	v_cvt_pk_bf16_f32 v76, v38, v39
	v_cvt_pk_bf16_f32 v77, v40, v41
	global_store_dwordx2 v[80:81], v[76:77], off offset:1024 nt
	v_cvt_pk_bf16_f32 v76, v18, v19
	v_cvt_pk_bf16_f32 v77, v20, v21
	global_store_dwordx2 v[80:81], v[76:77], off offset:1536 nt
	v_cvt_pk_bf16_f32 v76, v14, v15
	v_cvt_pk_bf16_f32 v77, v16, v17
	global_store_dwordx2 v[80:81], v[76:77], off offset:2048 nt
	v_cvt_pk_bf16_f32 v76, v10, v11
	v_cvt_pk_bf16_f32 v77, v12, v13
	global_store_dwordx2 v[80:81], v[76:77], off offset:2560 nt
	v_cvt_pk_bf16_f32 v76, v6, v7
	v_cvt_pk_bf16_f32 v77, v8, v9
	global_store_dwordx2 v[80:81], v[76:77], off offset:3072 nt
	v_cvt_pk_bf16_f32 v76, v2, v3
	v_cvt_pk_bf16_f32 v77, v4, v5
	global_store_dwordx2 v[80:81], v[76:77], off offset:3584 nt
	s_and_saveexec_b64 s[30:31], s[4:5]
	s_cbranch_execz .LBB0_458
	s_waitcnt lgkmcnt(0)
	v_add_f32_e32 v68, v74, v75
	v_mul_f32_e32 v68, 0x4e800000, v68
	v_trunc_f32_e32 v68, v68
	v_mul_f32_e64 v74, |v68|, s38
	v_floor_f32_e32 v74, v74
	v_fma_f32 v75, v74, s39, |v68|
	v_cvt_u32_f32_e32 v74, v74
	v_cvt_u32_f32_e32 v75, v75
	v_ashrrev_i32_e32 v68, 31, v68
	s_lshl_b64 s[34:35], s[8:9], 3
	v_xor_b32_e32 v76, v74, v68
	v_xor_b32_e32 v74, v75, v68
	v_sub_co_u32_e32 v74, vcc, v74, v68
	s_add_u32 s28, s28, s34
	s_nop 0
	v_subb_co_u32_e32 v75, vcc, v76, v68, vcc
	s_addc_u32 s29, s29, s35
	global_store_dwordx2 v67, v[74:75], s[28:29] nt

.LBB0_459:
	s_andn2_b64 vcc, exec, s[28:29]
	s_cbranch_vccnz .LBB0_442
	s_cmpk_gt_i32 s26, 0x207f
	s_cselect_b64 s[26:27], -1, 0
	s_waitcnt vmcnt(8)
	v_cndmask_b32_e64 v65, v65, 0, s[26:27]
	v_cndmask_b32_e64 v63, v63, 0, s[26:27]
	v_cndmask_b32_e64 v64, v64, 0, s[26:27]
	v_cndmask_b32_e64 v62, v62, 0, s[26:27]
	v_mul_f32_e32 v68, v63, v63
	v_mul_f32_e32 v74, v65, v65
	v_fmac_f32_e32 v68, v62, v62
	v_fmac_f32_e32 v74, v64, v64
	v_cndmask_b32_e64 v61, v61, 0, s[26:27]
	v_cndmask_b32_e64 v59, v59, 0, s[26:27]
	v_add_f32_e32 v68, v68, v74
	v_cndmask_b32_e64 v60, v60, 0, s[26:27]
	v_cndmask_b32_e64 v58, v58, 0, s[26:27]
	v_mul_f32_e32 v74, v59, v59
	s_waitcnt lgkmcnt(0)
	v_mul_f32_e32 v75, v61, v61
	v_fmac_f32_e32 v74, v58, v58
	v_fmac_f32_e32 v75, v60, v60
	v_add_f32_e32 v74, v74, v75
	v_cndmask_b32_e64 v41, v41, 0, s[26:27]
	v_cndmask_b32_e64 v39, v39, 0, s[26:27]
	v_add_f32_e32 v68, v68, v74
	v_cndmask_b32_e64 v40, v40, 0, s[26:27]
	v_cndmask_b32_e64 v38, v38, 0, s[26:27]
	v_mul_f32_e32 v74, v39, v39
	v_mul_f32_e32 v75, v41, v41
	v_fmac_f32_e32 v74, v38, v38
	v_fmac_f32_e32 v75, v40, v40
	v_add_f32_e32 v74, v74, v75
	v_cndmask_b32_e64 v21, v21, 0, s[26:27]
	v_cndmask_b32_e64 v19, v19, 0, s[26:27]
	v_add_f32_e32 v68, v68, v74
	v_cndmask_b32_e64 v20, v20, 0, s[26:27]
	v_cndmask_b32_e64 v18, v18, 0, s[26:27]
	v_mul_f32_e32 v74, v19, v19
	v_mul_f32_e32 v75, v21, v21
	v_fmac_f32_e32 v74, v18, v18
	v_fmac_f32_e32 v75, v20, v20
	v_add_f32_e32 v74, v74, v75
	v_cndmask_b32_e64 v17, v17, 0, s[26:27]
	v_cndmask_b32_e64 v15, v15, 0, s[26:27]
	v_add_f32_e32 v68, v68, v74
	v_cndmask_b32_e64 v16, v16, 0, s[26:27]
	v_cndmask_b32_e64 v14, v14, 0, s[26:27]
	v_mul_f32_e32 v74, v15, v15
	v_mul_f32_e32 v75, v17, v17
	v_fmac_f32_e32 v74, v14, v14
	v_fmac_f32_e32 v75, v16, v16
	v_add_f32_e32 v74, v74, v75
	v_cndmask_b32_e64 v13, v13, 0, s[26:27]
	v_cndmask_b32_e64 v11, v11, 0, s[26:27]
	v_add_f32_e32 v68, v68, v74
	v_cndmask_b32_e64 v12, v12, 0, s[26:27]
	v_cndmask_b32_e64 v10, v10, 0, s[26:27]
	v_mul_f32_e32 v74, v11, v11
	v_mul_f32_e32 v75, v13, v13
	v_fmac_f32_e32 v74, v10, v10
	v_fmac_f32_e32 v75, v12, v12
	v_add_f32_e32 v74, v74, v75
	v_cndmask_b32_e64 v9, v9, 0, s[26:27]
	v_cndmask_b32_e64 v75, v7, 0, s[26:27]
	v_add_f32_e32 v68, v68, v74
	v_cndmask_b32_e64 v8, v8, 0, s[26:27]
	v_cndmask_b32_e64 v74, v6, 0, s[26:27]
	v_mul_f32_e32 v6, v75, v75
	v_mul_f32_e32 v7, v9, v9
	v_fmac_f32_e32 v6, v74, v74
	v_fmac_f32_e32 v7, v8, v8
	v_add_f32_e32 v6, v6, v7
	v_cndmask_b32_e64 v76, v5, 0, s[26:27]
	v_cndmask_b32_e64 v78, v3, 0, s[26:27]
	v_add_f32_e32 v6, v68, v6
	v_cndmask_b32_e64 v68, v4, 0, s[26:27]
	v_cndmask_b32_e64 v77, v2, 0, s[26:27]
	v_mul_f32_e32 v2, v78, v78
	v_mul_f32_e32 v3, v76, v76
	v_fmac_f32_e32 v2, v77, v77
	v_fmac_f32_e32 v3, v68, v68
	v_add_f32_e32 v2, v2, v3
	v_and_b32_e32 v3, 64, v73
	v_add_u32_e32 v3, 64, v3
	v_xor_b32_e32 v4, 1, v73
	v_cmp_lt_i32_e32 vcc, v4, v3
	v_add_f32_e32 v2, v6, v2
	s_load_dwordx2 s[26:27], s[14:15], 0x118
	v_cndmask_b32_e32 v4, v73, v4, vcc
	v_lshlrev_b32_e32 v4, 2, v4
	ds_bpermute_b32 v4, v4, v2
	s_waitcnt lgkmcnt(0)
	v_lshl_add_u64 v[6:7], s[26:27], 0, v[70:71]
	v_add_f32_e32 v2, v2, v4
	v_xor_b32_e32 v4, 2, v73
	v_cmp_lt_i32_e32 vcc, v4, v3
	s_nop 1
	v_cndmask_b32_e32 v4, v73, v4, vcc
	v_lshlrev_b32_e32 v4, 2, v4
	ds_bpermute_b32 v4, v4, v2
	s_waitcnt lgkmcnt(0)
	v_add_f32_e32 v2, v2, v4
	v_xor_b32_e32 v4, 4, v73
	v_cmp_lt_i32_e32 vcc, v4, v3
	s_nop 1
	v_cndmask_b32_e32 v4, v73, v4, vcc
	v_lshlrev_b32_e32 v4, 2, v4
	ds_bpermute_b32 v4, v4, v2
	s_waitcnt lgkmcnt(0)
	v_add_f32_e32 v2, v2, v4
	v_xor_b32_e32 v4, 8, v73
	v_cmp_lt_i32_e32 vcc, v4, v3
	s_nop 1
	v_cndmask_b32_e32 v4, v73, v4, vcc
	v_lshlrev_b32_e32 v4, 2, v4
	ds_bpermute_b32 v4, v4, v2
	s_waitcnt lgkmcnt(0)
	v_add_f32_e32 v2, v2, v4
	v_xor_b32_e32 v4, 16, v73
	v_cmp_lt_i32_e32 vcc, v4, v3
	s_nop 1
	v_cndmask_b32_e32 v4, v73, v4, vcc
	v_lshlrev_b32_e32 v4, 2, v4
	ds_bpermute_b32 v4, v4, v2
	s_waitcnt lgkmcnt(0)
	v_add_f32_e32 v2, v2, v4
	v_xor_b32_e32 v4, 32, v73
	v_cmp_lt_i32_e32 vcc, v4, v3
	s_nop 1
	v_cndmask_b32_e32 v3, v73, v4, vcc
	v_cvt_pk_bf16_f32 v4, v62, v63
	v_cvt_pk_bf16_f32 v5, v64, v65
	v_lshlrev_b32_e32 v3, 2, v3
	global_store_dwordx2 v[6:7], v[4:5], off nt
	v_cvt_pk_bf16_f32 v4, v58, v59
	v_cvt_pk_bf16_f32 v5, v60, v61
	ds_bpermute_b32 v3, v3, v2
	global_store_dwordx2 v[6:7], v[4:5], off offset:512 nt
	v_cvt_pk_bf16_f32 v4, v38, v39
	v_cvt_pk_bf16_f32 v5, v40, v41
	global_store_dwordx2 v[6:7], v[4:5], off offset:1024 nt
	v_cvt_pk_bf16_f32 v4, v18, v19
	v_cvt_pk_bf16_f32 v5, v20, v21
	global_store_dwordx2 v[6:7], v[4:5], off offset:1536 nt
	v_cvt_pk_bf16_f32 v4, v14, v15
	v_cvt_pk_bf16_f32 v5, v16, v17
	global_store_dwordx2 v[6:7], v[4:5], off offset:2048 nt
	v_cvt_pk_bf16_f32 v4, v10, v11
	v_cvt_pk_bf16_f32 v5, v12, v13
	global_store_dwordx2 v[6:7], v[4:5], off offset:2560 nt
	v_cvt_pk_bf16_f32 v4, v74, v75
	v_cvt_pk_bf16_f32 v5, v8, v9
	global_store_dwordx2 v[6:7], v[4:5], off offset:3072 nt
	v_cvt_pk_bf16_f32 v4, v77, v78
	v_cvt_pk_bf16_f32 v5, v68, v76
	global_store_dwordx2 v[6:7], v[4:5], off offset:3584 nt
	s_and_saveexec_b64 s[28:29], s[4:5]
	s_cbranch_execz .LBB0_441
	s_waitcnt lgkmcnt(0)
	v_add_f32_e32 v2, v2, v3
	v_mul_f32_e32 v2, 0x4e800000, v2
	v_trunc_f32_e32 v2, v2
	v_mul_f32_e64 v3, |v2|, s38
	v_floor_f32_e32 v3, v3
	v_fma_f32 v4, v3, s39, |v2|
	v_cvt_u32_f32_e32 v4, v4
	v_cvt_u32_f32_e32 v3, v3
	v_ashrrev_i32_e32 v5, 31, v2
	s_add_u32 s26, s26, s36
	v_xor_b32_e32 v2, v4, v5
	v_xor_b32_e32 v3, v3, v5
	v_sub_co_u32_e32 v2, vcc, v2, v5
	s_addc_u32 s27, s27, s37
	s_nop 0
	v_subb_co_u32_e32 v3, vcc, v3, v5, vcc
	global_store_dwordx2 v69, v[2:3], s[26:27] nt
	s_branch .LBB0_441

.LBB0_464:
	v_ashrrev_i32_e32 v3, 31, v2
	s_waitcnt lgkmcnt(0)
	v_lshl_add_u64 v[4:5], v[2:3], 2, s[18:19]
	global_load_dwordx4 v[4:7], v[4:5], off
	s_waitcnt vmcnt(7)
	v_bfe_u32 v9, v1, 5, 7
	v_add_u32_e32 v1, s24, v1
	v_and_b32_e32 v8, 0x7c, v2
	v_cmp_lt_i32_e32 vcc, s25, v1
	s_waitcnt vmcnt(6)
	v_or_b32_e32 v10, 2, v8
	v_or_b32_e32 v11, 3, v8
	v_cmp_lt_u32_e64 s[4:5], v8, v9
	s_or_b64 s[22:23], vcc, s[22:23]
	v_cmp_le_u32_e32 vcc, v8, v9
	v_cmp_le_u32_e64 s[6:7], v10, v9
	v_cmp_le_u32_e64 s[8:9], v11, v9
	s_waitcnt vmcnt(0)
	v_cndmask_b32_e32 v4, 0, v4, vcc
	v_cndmask_b32_e64 v5, 0, v5, s[4:5]
	v_cndmask_b32_e64 v6, 0, v6, s[6:7]
	v_cndmask_b32_e64 v7, 0, v7, s[8:9]
	v_cvt_pk_bf16_f32 v4, v4, v5
	v_cvt_pk_bf16_f32 v5, v6, v7
	s_load_dwordx2 s[4:5], s[14:15], 0x118
	s_waitcnt lgkmcnt(0)
	v_lshl_add_u64 v[6:7], v[2:3], 1, s[4:5]
	v_add_co_u32_e32 v6, vcc, 0x16800000, v6
	v_add_u32_e32 v2, s21, v2
	s_nop 0
	v_addc_co_u32_e32 v7, vcc, 0, v7, vcc
	global_store_dwordx2 v[6:7], v[4:5], off nt
	s_andn2_b64 exec, exec, s[22:23]
	s_cbranch_execnz .LBB0_464
